# scan waves: operand prefetch distance 2 (third rotating operand register set v186-201), counted waits; same arithmetic
# speedup vs baseline: 1.0092x; 1.0092x over previous
.LBB0_650:
	s_andn2_saveexec_b64 s[46:47], s[46:47]
	s_cbranch_execz .LBB0_652
	v_add_u32_e32 v136, 0xa000, v95
	ds_read_b128 v[28:31], v92 offset:256
	ds_read_b128 v[102:105], v92 offset:768
	ds_read_b128 v[24:27], v92 offset:0
	ds_read_b128 v[98:101], v92 offset:512
	ds_read_b128 v[106:109], v92 offset:1024
	ds_read2_b32 v[130:131], v136 offset0:0 offset1:16
	ds_read_b128 v[114:117], v92 offset:1536
	ds_read_b128 v[122:125], v92 offset:2048
	ds_read_b128 v[110:113], v92 offset:1280
	ds_read_b128 v[118:121], v92 offset:1792
	ds_read_b128 v[126:129], v92 offset:2304
	ds_read_b128 v[190:193], v92 offset:2816
	ds_read_b128 v[198:201], v92 offset:3328
	ds_read_b128 v[186:189], v92 offset:2560
	ds_read_b128 v[194:197], v92 offset:3072
	ds_read_b128 v[50:53], v92 offset:3584
	ds_read2_b32 v[132:133], v136 offset0:32 offset1:48
	s_waitcnt lgkmcnt(11)
	v_pk_mul_f32 v[36:37], v[90:91], v[28:29]
	v_pk_fma_f32 v[36:37], v[88:89], v[30:31], v[36:37]
	v_add_f32_e32 v38, v36, v37
	v_pk_mul_f32 v[40:41], v[102:103], v[130:131] op_sel_hi:[1,0]
	v_pk_mul_f32 v[42:43], v[104:105], v[130:131] op_sel_hi:[1,0]
	v_add_f32_dpp v38, v38, v38 quad_perm:[1,0,3,2] row_mask:0xf bank_mask:0xf bound_ctrl:1
	v_pk_fma_f32 v[40:41], v[90:91], v[24:25], v[40:41]
	v_pk_fma_f32 v[42:43], v[88:89], v[26:27], v[42:43]
	v_add_f32_dpp v38, v38, v38 quad_perm:[2,3,0,1] row_mask:0xf bank_mask:0xf bound_ctrl:1
	s_nop 1
	v_add_f32_dpp v38, v38, v38 row_half_mirror row_mask:0xf bank_mask:0xf bound_ctrl:1
	s_nop 1
	v_add_f32_dpp v38, v38, v38 row_mirror row_mask:0xf bank_mask:0xf bound_ctrl:1
	v_pk_fma_f32 v[90:91], v[98:99], v[38:39], v[40:41] op_sel_hi:[1,0,1]
	v_pk_fma_f32 v[88:89], v[100:101], v[38:39], v[42:43] op_sel_hi:[1,0,1]
	ds_read_b128 v[28:31], v92 offset:4096
	ds_read_b128 v[102:105], v92 offset:4608
	ds_read_b128 v[24:27], v92 offset:3840
	ds_read_b128 v[98:101], v92 offset:4352
	ds_read_b128 v[54:57], v92 offset:4864
	s_waitcnt lgkmcnt(11)
	v_pk_mul_f32 v[36:37], v[90:91], v[114:115]
	v_pk_fma_f32 v[36:37], v[88:89], v[116:117], v[36:37]
	v_add_f32_e32 v38, v36, v37
	v_pk_mul_f32 v[40:41], v[122:123], v[130:131] op_sel:[0,1] op_sel_hi:[1,1]
	v_pk_mul_f32 v[42:43], v[124:125], v[130:131] op_sel:[0,1] op_sel_hi:[1,1]
	v_add_f32_dpp v38, v38, v38 quad_perm:[1,0,3,2] row_mask:0xf bank_mask:0xf bound_ctrl:1
	v_pk_fma_f32 v[40:41], v[90:91], v[110:111], v[40:41]
	v_pk_fma_f32 v[42:43], v[88:89], v[112:113], v[42:43]
	v_add_f32_dpp v38, v38, v38 quad_perm:[2,3,0,1] row_mask:0xf bank_mask:0xf bound_ctrl:1
	v_pk_mul_f32 v[44:45], v[90:91], v[106:107]
	v_pk_fma_f32 v[44:45], v[88:89], v[108:109], v[44:45]
	v_add_f32_dpp v38, v38, v38 row_half_mirror row_mask:0xf bank_mask:0xf bound_ctrl:1
	v_add_f32_e32 v46, v44, v45
	s_nop 0
	v_add_f32_dpp v38, v38, v38 row_mirror row_mask:0xf bank_mask:0xf bound_ctrl:1
	v_pk_fma_f32 v[90:91], v[118:119], v[38:39], v[40:41] op_sel_hi:[1,0,1]
	v_pk_fma_f32 v[88:89], v[120:121], v[38:39], v[42:43] op_sel_hi:[1,0,1]
	ds_read_b128 v[114:117], v92 offset:5376
	ds_read_b128 v[122:125], v92 offset:5888
	ds_read_b128 v[110:113], v92 offset:5120
	ds_read_b128 v[118:121], v92 offset:5632
	ds_read_b128 v[106:109], v92 offset:6144
	ds_read2_b32 v[130:131], v136 offset0:64 offset1:80
	s_waitcnt lgkmcnt(11)
	v_pk_mul_f32 v[36:37], v[90:91], v[190:191]
	v_pk_fma_f32 v[36:37], v[88:89], v[192:193], v[36:37]
	v_add_f32_e32 v38, v36, v37
	v_pk_mul_f32 v[40:41], v[198:199], v[132:133] op_sel_hi:[1,0]
	v_pk_mul_f32 v[42:43], v[200:201], v[132:133] op_sel_hi:[1,0]
	v_add_f32_dpp v38, v38, v38 quad_perm:[1,0,3,2] row_mask:0xf bank_mask:0xf bound_ctrl:1
	v_pk_fma_f32 v[40:41], v[90:91], v[186:187], v[40:41]
	v_pk_fma_f32 v[42:43], v[88:89], v[188:189], v[42:43]
	v_add_f32_dpp v38, v38, v38 quad_perm:[2,3,0,1] row_mask:0xf bank_mask:0xf bound_ctrl:1
	v_pk_mul_f32 v[44:45], v[90:91], v[126:127]
	v_pk_fma_f32 v[44:45], v[88:89], v[128:129], v[44:45]
	v_add_f32_dpp v38, v38, v38 row_half_mirror row_mask:0xf bank_mask:0xf bound_ctrl:1
	v_add_f32_e32 v47, v44, v45
	s_nop 0
	v_add_f32_dpp v38, v38, v38 row_mirror row_mask:0xf bank_mask:0xf bound_ctrl:1
	v_pk_fma_f32 v[90:91], v[194:195], v[38:39], v[40:41] op_sel_hi:[1,0,1]
	v_pk_fma_f32 v[88:89], v[196:197], v[38:39], v[42:43] op_sel_hi:[1,0,1]
	ds_read_b128 v[190:193], v92 offset:6656
	ds_read_b128 v[198:201], v92 offset:7168
	ds_read_b128 v[186:189], v92 offset:6400
	ds_read_b128 v[194:197], v92 offset:6912
	ds_read_b128 v[126:129], v92 offset:7424
	ds_write2st64_b32 v96, v46, v47 offset0:168 offset1:172
	s_waitcnt lgkmcnt(12)
	v_pk_mul_f32 v[36:37], v[90:91], v[28:29]
	v_pk_fma_f32 v[36:37], v[88:89], v[30:31], v[36:37]
	v_add_f32_e32 v38, v36, v37
	v_pk_mul_f32 v[40:41], v[102:103], v[132:133] op_sel:[0,1] op_sel_hi:[1,1]
	v_pk_mul_f32 v[42:43], v[104:105], v[132:133] op_sel:[0,1] op_sel_hi:[1,1]
	v_add_f32_dpp v38, v38, v38 quad_perm:[1,0,3,2] row_mask:0xf bank_mask:0xf bound_ctrl:1
	v_pk_fma_f32 v[40:41], v[90:91], v[24:25], v[40:41]
	v_pk_fma_f32 v[42:43], v[88:89], v[26:27], v[42:43]
	v_add_f32_dpp v38, v38, v38 quad_perm:[2,3,0,1] row_mask:0xf bank_mask:0xf bound_ctrl:1
	v_pk_mul_f32 v[44:45], v[90:91], v[50:51]
	v_pk_fma_f32 v[44:45], v[88:89], v[52:53], v[44:45]
	v_add_f32_dpp v38, v38, v38 row_half_mirror row_mask:0xf bank_mask:0xf bound_ctrl:1
	v_add_f32_e32 v48, v44, v45
	s_nop 0
	v_add_f32_dpp v38, v38, v38 row_mirror row_mask:0xf bank_mask:0xf bound_ctrl:1
	v_pk_fma_f32 v[90:91], v[98:99], v[38:39], v[40:41] op_sel_hi:[1,0,1]
	v_pk_fma_f32 v[88:89], v[100:101], v[38:39], v[42:43] op_sel_hi:[1,0,1]
	ds_read_b128 v[28:31], v92 offset:7936
	ds_read_b128 v[102:105], v92 offset:8448
	ds_read_b128 v[24:27], v92 offset:7680
	ds_read_b128 v[98:101], v92 offset:8192
	ds_read_b128 v[50:53], v92 offset:8704
	ds_read2_b32 v[132:133], v136 offset0:96 offset1:112
	s_waitcnt lgkmcnt(12)
	v_pk_mul_f32 v[36:37], v[90:91], v[114:115]
	v_pk_fma_f32 v[36:37], v[88:89], v[116:117], v[36:37]
	v_add_f32_e32 v38, v36, v37
	v_pk_mul_f32 v[40:41], v[122:123], v[130:131] op_sel_hi:[1,0]
	v_pk_mul_f32 v[42:43], v[124:125], v[130:131] op_sel_hi:[1,0]
	v_add_f32_dpp v38, v38, v38 quad_perm:[1,0,3,2] row_mask:0xf bank_mask:0xf bound_ctrl:1
	v_pk_fma_f32 v[40:41], v[90:91], v[110:111], v[40:41]
	v_pk_fma_f32 v[42:43], v[88:89], v[112:113], v[42:43]
	v_add_f32_dpp v38, v38, v38 quad_perm:[2,3,0,1] row_mask:0xf bank_mask:0xf bound_ctrl:1
	v_pk_mul_f32 v[44:45], v[90:91], v[54:55]
	v_pk_fma_f32 v[44:45], v[88:89], v[56:57], v[44:45]
	v_add_f32_dpp v38, v38, v38 row_half_mirror row_mask:0xf bank_mask:0xf bound_ctrl:1
	v_add_f32_e32 v49, v44, v45
	s_nop 0
	v_add_f32_dpp v38, v38, v38 row_mirror row_mask:0xf bank_mask:0xf bound_ctrl:1
	v_pk_fma_f32 v[90:91], v[118:119], v[38:39], v[40:41] op_sel_hi:[1,0,1]
	v_pk_fma_f32 v[88:89], v[120:121], v[38:39], v[42:43] op_sel_hi:[1,0,1]
	ds_read_b128 v[114:117], v92 offset:9216
	ds_read_b128 v[122:125], v92 offset:9728
	ds_read_b128 v[110:113], v92 offset:8960
	ds_read_b128 v[118:121], v92 offset:9472
	ds_read_b128 v[54:57], v92 offset:9984
	ds_write2st64_b32 v96, v48, v49 offset0:176 offset1:180
	s_waitcnt lgkmcnt(12)
	v_pk_mul_f32 v[36:37], v[90:91], v[190:191]
	v_pk_fma_f32 v[36:37], v[88:89], v[192:193], v[36:37]
	v_add_f32_e32 v38, v36, v37
	v_pk_mul_f32 v[40:41], v[198:199], v[130:131] op_sel:[0,1] op_sel_hi:[1,1]
	v_pk_mul_f32 v[42:43], v[200:201], v[130:131] op_sel:[0,1] op_sel_hi:[1,1]
	v_add_f32_dpp v38, v38, v38 quad_perm:[1,0,3,2] row_mask:0xf bank_mask:0xf bound_ctrl:1
	v_pk_fma_f32 v[40:41], v[90:91], v[186:187], v[40:41]
	v_pk_fma_f32 v[42:43], v[88:89], v[188:189], v[42:43]
	v_add_f32_dpp v38, v38, v38 quad_perm:[2,3,0,1] row_mask:0xf bank_mask:0xf bound_ctrl:1
	v_pk_mul_f32 v[44:45], v[90:91], v[106:107]
	v_pk_fma_f32 v[44:45], v[88:89], v[108:109], v[44:45]
	v_add_f32_dpp v38, v38, v38 row_half_mirror row_mask:0xf bank_mask:0xf bound_ctrl:1
	v_add_f32_e32 v46, v44, v45
	s_nop 0
	v_add_f32_dpp v38, v38, v38 row_mirror row_mask:0xf bank_mask:0xf bound_ctrl:1
	v_pk_fma_f32 v[90:91], v[194:195], v[38:39], v[40:41] op_sel_hi:[1,0,1]
	v_pk_fma_f32 v[88:89], v[196:197], v[38:39], v[42:43] op_sel_hi:[1,0,1]
	ds_read_b128 v[190:193], v92 offset:10496
	ds_read_b128 v[198:201], v92 offset:11008
	ds_read_b128 v[186:189], v92 offset:10240
	ds_read_b128 v[194:197], v92 offset:10752
	ds_read_b128 v[106:109], v92 offset:11264
	ds_read2_b32 v[130:131], v136 offset0:128 offset1:144
	s_waitcnt lgkmcnt(12)
	v_pk_mul_f32 v[36:37], v[90:91], v[28:29]
	v_pk_fma_f32 v[36:37], v[88:89], v[30:31], v[36:37]
	v_add_f32_e32 v38, v36, v37
	v_pk_mul_f32 v[40:41], v[102:103], v[132:133] op_sel_hi:[1,0]
	v_pk_mul_f32 v[42:43], v[104:105], v[132:133] op_sel_hi:[1,0]
	v_add_f32_dpp v38, v38, v38 quad_perm:[1,0,3,2] row_mask:0xf bank_mask:0xf bound_ctrl:1
	v_pk_fma_f32 v[40:41], v[90:91], v[24:25], v[40:41]
	v_pk_fma_f32 v[42:43], v[88:89], v[26:27], v[42:43]
	v_add_f32_dpp v38, v38, v38 quad_perm:[2,3,0,1] row_mask:0xf bank_mask:0xf bound_ctrl:1
	v_pk_mul_f32 v[44:45], v[90:91], v[126:127]
	v_pk_fma_f32 v[44:45], v[88:89], v[128:129], v[44:45]
	v_add_f32_dpp v38, v38, v38 row_half_mirror row_mask:0xf bank_mask:0xf bound_ctrl:1
	v_add_f32_e32 v47, v44, v45
	s_nop 0
	v_add_f32_dpp v38, v38, v38 row_mirror row_mask:0xf bank_mask:0xf bound_ctrl:1
	v_pk_fma_f32 v[90:91], v[98:99], v[38:39], v[40:41] op_sel_hi:[1,0,1]
	v_pk_fma_f32 v[88:89], v[100:101], v[38:39], v[42:43] op_sel_hi:[1,0,1]
	ds_read_b128 v[28:31], v92 offset:11776
	ds_read_b128 v[102:105], v92 offset:12288
	ds_read_b128 v[24:27], v92 offset:11520
	ds_read_b128 v[98:101], v92 offset:12032
	ds_read_b128 v[126:129], v92 offset:12544
	ds_write2st64_b32 v96, v46, v47 offset0:184 offset1:188
	s_waitcnt lgkmcnt(12)
	v_pk_mul_f32 v[36:37], v[90:91], v[114:115]
	v_pk_fma_f32 v[36:37], v[88:89], v[116:117], v[36:37]
	v_add_f32_e32 v38, v36, v37
	v_pk_mul_f32 v[40:41], v[122:123], v[132:133] op_sel:[0,1] op_sel_hi:[1,1]
	v_pk_mul_f32 v[42:43], v[124:125], v[132:133] op_sel:[0,1] op_sel_hi:[1,1]
	v_add_f32_dpp v38, v38, v38 quad_perm:[1,0,3,2] row_mask:0xf bank_mask:0xf bound_ctrl:1
	v_pk_fma_f32 v[40:41], v[90:91], v[110:111], v[40:41]
	v_pk_fma_f32 v[42:43], v[88:89], v[112:113], v[42:43]
	v_add_f32_dpp v38, v38, v38 quad_perm:[2,3,0,1] row_mask:0xf bank_mask:0xf bound_ctrl:1
	v_pk_mul_f32 v[44:45], v[90:91], v[50:51]
	v_pk_fma_f32 v[44:45], v[88:89], v[52:53], v[44:45]
	v_add_f32_dpp v38, v38, v38 row_half_mirror row_mask:0xf bank_mask:0xf bound_ctrl:1
	v_add_f32_e32 v48, v44, v45
	s_nop 0
	v_add_f32_dpp v38, v38, v38 row_mirror row_mask:0xf bank_mask:0xf bound_ctrl:1
	v_pk_fma_f32 v[90:91], v[118:119], v[38:39], v[40:41] op_sel_hi:[1,0,1]
	v_pk_fma_f32 v[88:89], v[120:121], v[38:39], v[42:43] op_sel_hi:[1,0,1]
	ds_read_b128 v[114:117], v92 offset:13056
	ds_read_b128 v[122:125], v92 offset:13568
	ds_read_b128 v[110:113], v92 offset:12800
	ds_read_b128 v[118:121], v92 offset:13312
	ds_read_b128 v[50:53], v92 offset:13824
	ds_read2_b32 v[132:133], v136 offset0:160 offset1:176
	s_waitcnt lgkmcnt(12)
	v_pk_mul_f32 v[36:37], v[90:91], v[190:191]
	v_pk_fma_f32 v[36:37], v[88:89], v[192:193], v[36:37]
	v_add_f32_e32 v38, v36, v37
	v_pk_mul_f32 v[40:41], v[198:199], v[130:131] op_sel_hi:[1,0]
	v_pk_mul_f32 v[42:43], v[200:201], v[130:131] op_sel_hi:[1,0]
	v_add_f32_dpp v38, v38, v38 quad_perm:[1,0,3,2] row_mask:0xf bank_mask:0xf bound_ctrl:1
	v_pk_fma_f32 v[40:41], v[90:91], v[186:187], v[40:41]
	v_pk_fma_f32 v[42:43], v[88:89], v[188:189], v[42:43]
	v_add_f32_dpp v38, v38, v38 quad_perm:[2,3,0,1] row_mask:0xf bank_mask:0xf bound_ctrl:1
	v_pk_mul_f32 v[44:45], v[90:91], v[54:55]
	v_pk_fma_f32 v[44:45], v[88:89], v[56:57], v[44:45]
	v_add_f32_dpp v38, v38, v38 row_half_mirror row_mask:0xf bank_mask:0xf bound_ctrl:1
	v_add_f32_e32 v49, v44, v45
	s_nop 0
	v_add_f32_dpp v38, v38, v38 row_mirror row_mask:0xf bank_mask:0xf bound_ctrl:1
	v_pk_fma_f32 v[90:91], v[194:195], v[38:39], v[40:41] op_sel_hi:[1,0,1]
	v_pk_fma_f32 v[88:89], v[196:197], v[38:39], v[42:43] op_sel_hi:[1,0,1]
	ds_read_b128 v[190:193], v92 offset:14336
	ds_read_b128 v[198:201], v92 offset:14848
	ds_read_b128 v[186:189], v92 offset:14080
	ds_read_b128 v[194:197], v92 offset:14592
	ds_read_b128 v[54:57], v92 offset:15104
	ds_write2st64_b32 v96, v48, v49 offset0:192 offset1:196
	s_waitcnt lgkmcnt(12)
	v_pk_mul_f32 v[36:37], v[90:91], v[28:29]
	v_pk_fma_f32 v[36:37], v[88:89], v[30:31], v[36:37]
	v_add_f32_e32 v38, v36, v37
	v_pk_mul_f32 v[40:41], v[102:103], v[130:131] op_sel:[0,1] op_sel_hi:[1,1]
	v_pk_mul_f32 v[42:43], v[104:105], v[130:131] op_sel:[0,1] op_sel_hi:[1,1]
	v_add_f32_dpp v38, v38, v38 quad_perm:[1,0,3,2] row_mask:0xf bank_mask:0xf bound_ctrl:1
	v_pk_fma_f32 v[40:41], v[90:91], v[24:25], v[40:41]
	v_pk_fma_f32 v[42:43], v[88:89], v[26:27], v[42:43]
	v_add_f32_dpp v38, v38, v38 quad_perm:[2,3,0,1] row_mask:0xf bank_mask:0xf bound_ctrl:1
	v_pk_mul_f32 v[44:45], v[90:91], v[106:107]
	v_pk_fma_f32 v[44:45], v[88:89], v[108:109], v[44:45]
	v_add_f32_dpp v38, v38, v38 row_half_mirror row_mask:0xf bank_mask:0xf bound_ctrl:1
	v_add_f32_e32 v46, v44, v45
	s_nop 0
	v_add_f32_dpp v38, v38, v38 row_mirror row_mask:0xf bank_mask:0xf bound_ctrl:1
	v_pk_fma_f32 v[90:91], v[98:99], v[38:39], v[40:41] op_sel_hi:[1,0,1]
	v_pk_fma_f32 v[88:89], v[100:101], v[38:39], v[42:43] op_sel_hi:[1,0,1]
	ds_read_b128 v[28:31], v92 offset:15616
	ds_read_b128 v[102:105], v92 offset:16128
	ds_read_b128 v[24:27], v92 offset:15360
	ds_read_b128 v[98:101], v92 offset:15872
	ds_read_b128 v[106:109], v92 offset:16384
	ds_read2_b32 v[130:131], v136 offset0:192 offset1:208
	s_waitcnt lgkmcnt(12)
	v_pk_mul_f32 v[36:37], v[90:91], v[114:115]
	v_pk_fma_f32 v[36:37], v[88:89], v[116:117], v[36:37]
	v_add_f32_e32 v38, v36, v37
	v_pk_mul_f32 v[40:41], v[122:123], v[132:133] op_sel_hi:[1,0]
	v_pk_mul_f32 v[42:43], v[124:125], v[132:133] op_sel_hi:[1,0]
	v_add_f32_dpp v38, v38, v38 quad_perm:[1,0,3,2] row_mask:0xf bank_mask:0xf bound_ctrl:1
	v_pk_fma_f32 v[40:41], v[90:91], v[110:111], v[40:41]
	v_pk_fma_f32 v[42:43], v[88:89], v[112:113], v[42:43]
	v_add_f32_dpp v38, v38, v38 quad_perm:[2,3,0,1] row_mask:0xf bank_mask:0xf bound_ctrl:1
	v_pk_mul_f32 v[44:45], v[90:91], v[126:127]
	v_pk_fma_f32 v[44:45], v[88:89], v[128:129], v[44:45]
	v_add_f32_dpp v38, v38, v38 row_half_mirror row_mask:0xf bank_mask:0xf bound_ctrl:1
	v_add_f32_e32 v47, v44, v45
	s_nop 0
	v_add_f32_dpp v38, v38, v38 row_mirror row_mask:0xf bank_mask:0xf bound_ctrl:1
	v_pk_fma_f32 v[90:91], v[118:119], v[38:39], v[40:41] op_sel_hi:[1,0,1]
	v_pk_fma_f32 v[88:89], v[120:121], v[38:39], v[42:43] op_sel_hi:[1,0,1]
	ds_read_b128 v[114:117], v92 offset:16896
	ds_read_b128 v[122:125], v92 offset:17408
	ds_read_b128 v[110:113], v92 offset:16640
	ds_read_b128 v[118:121], v92 offset:17152
	ds_read_b128 v[126:129], v92 offset:17664
	ds_write2st64_b32 v96, v46, v47 offset0:200 offset1:204
	s_waitcnt lgkmcnt(12)
	v_pk_mul_f32 v[36:37], v[90:91], v[190:191]
	v_pk_fma_f32 v[36:37], v[88:89], v[192:193], v[36:37]
	v_add_f32_e32 v38, v36, v37
	v_pk_mul_f32 v[40:41], v[198:199], v[132:133] op_sel:[0,1] op_sel_hi:[1,1]
	v_pk_mul_f32 v[42:43], v[200:201], v[132:133] op_sel:[0,1] op_sel_hi:[1,1]
	v_add_f32_dpp v38, v38, v38 quad_perm:[1,0,3,2] row_mask:0xf bank_mask:0xf bound_ctrl:1
	v_pk_fma_f32 v[40:41], v[90:91], v[186:187], v[40:41]
	v_pk_fma_f32 v[42:43], v[88:89], v[188:189], v[42:43]
	v_add_f32_dpp v38, v38, v38 quad_perm:[2,3,0,1] row_mask:0xf bank_mask:0xf bound_ctrl:1
	v_pk_mul_f32 v[44:45], v[90:91], v[50:51]
	v_pk_fma_f32 v[44:45], v[88:89], v[52:53], v[44:45]
	v_add_f32_dpp v38, v38, v38 row_half_mirror row_mask:0xf bank_mask:0xf bound_ctrl:1
	v_add_f32_e32 v48, v44, v45
	s_nop 0
	v_add_f32_dpp v38, v38, v38 row_mirror row_mask:0xf bank_mask:0xf bound_ctrl:1
	v_pk_fma_f32 v[90:91], v[194:195], v[38:39], v[40:41] op_sel_hi:[1,0,1]
	v_pk_fma_f32 v[88:89], v[196:197], v[38:39], v[42:43] op_sel_hi:[1,0,1]
	ds_read_b128 v[190:193], v92 offset:18176
	ds_read_b128 v[198:201], v92 offset:18688
	ds_read_b128 v[186:189], v92 offset:17920
	ds_read_b128 v[194:197], v92 offset:18432
	ds_read_b128 v[50:53], v92 offset:18944
	ds_read2_b32 v[132:133], v136 offset0:224 offset1:240
	s_waitcnt lgkmcnt(12)
	v_pk_mul_f32 v[36:37], v[90:91], v[28:29]
	v_pk_fma_f32 v[36:37], v[88:89], v[30:31], v[36:37]
	v_add_f32_e32 v38, v36, v37
	v_pk_mul_f32 v[40:41], v[102:103], v[130:131] op_sel_hi:[1,0]
	v_pk_mul_f32 v[42:43], v[104:105], v[130:131] op_sel_hi:[1,0]
	v_add_f32_dpp v38, v38, v38 quad_perm:[1,0,3,2] row_mask:0xf bank_mask:0xf bound_ctrl:1
	v_pk_fma_f32 v[40:41], v[90:91], v[24:25], v[40:41]
	v_pk_fma_f32 v[42:43], v[88:89], v[26:27], v[42:43]
	v_add_f32_dpp v38, v38, v38 quad_perm:[2,3,0,1] row_mask:0xf bank_mask:0xf bound_ctrl:1
	v_pk_mul_f32 v[44:45], v[90:91], v[54:55]
	v_pk_fma_f32 v[44:45], v[88:89], v[56:57], v[44:45]
	v_add_f32_dpp v38, v38, v38 row_half_mirror row_mask:0xf bank_mask:0xf bound_ctrl:1
	v_add_f32_e32 v49, v44, v45
	s_nop 0
	v_add_f32_dpp v38, v38, v38 row_mirror row_mask:0xf bank_mask:0xf bound_ctrl:1
	v_pk_fma_f32 v[90:91], v[98:99], v[38:39], v[40:41] op_sel_hi:[1,0,1]
	v_pk_fma_f32 v[88:89], v[100:101], v[38:39], v[42:43] op_sel_hi:[1,0,1]
	ds_read_b128 v[28:31], v92 offset:19456
	ds_read_b128 v[102:105], v92 offset:19968
	ds_read_b128 v[24:27], v92 offset:19200
	ds_read_b128 v[98:101], v92 offset:19712
	ds_read_b128 v[54:57], v92 offset:20224
	ds_write2st64_b32 v96, v48, v49 offset0:208 offset1:212
	s_waitcnt lgkmcnt(12)
	v_pk_mul_f32 v[36:37], v[90:91], v[114:115]
	v_pk_fma_f32 v[36:37], v[88:89], v[116:117], v[36:37]
	v_add_f32_e32 v38, v36, v37
	v_pk_mul_f32 v[40:41], v[122:123], v[130:131] op_sel:[0,1] op_sel_hi:[1,1]
	v_pk_mul_f32 v[42:43], v[124:125], v[130:131] op_sel:[0,1] op_sel_hi:[1,1]
	v_add_f32_dpp v38, v38, v38 quad_perm:[1,0,3,2] row_mask:0xf bank_mask:0xf bound_ctrl:1
	v_pk_fma_f32 v[40:41], v[90:91], v[110:111], v[40:41]
	v_pk_fma_f32 v[42:43], v[88:89], v[112:113], v[42:43]
	v_add_f32_dpp v38, v38, v38 quad_perm:[2,3,0,1] row_mask:0xf bank_mask:0xf bound_ctrl:1
	v_pk_mul_f32 v[44:45], v[90:91], v[106:107]
	v_pk_fma_f32 v[44:45], v[88:89], v[108:109], v[44:45]
	v_add_f32_dpp v38, v38, v38 row_half_mirror row_mask:0xf bank_mask:0xf bound_ctrl:1
	v_add_f32_e32 v46, v44, v45
	s_nop 0
	v_add_f32_dpp v38, v38, v38 row_mirror row_mask:0xf bank_mask:0xf bound_ctrl:1
	v_pk_fma_f32 v[90:91], v[118:119], v[38:39], v[40:41] op_sel_hi:[1,0,1]
	v_pk_fma_f32 v[88:89], v[120:121], v[38:39], v[42:43] op_sel_hi:[1,0,1]
	s_waitcnt lgkmcnt(6)
	v_pk_mul_f32 v[36:37], v[90:91], v[190:191]
	v_pk_fma_f32 v[36:37], v[88:89], v[192:193], v[36:37]
	v_add_f32_e32 v38, v36, v37
	v_pk_mul_f32 v[40:41], v[198:199], v[132:133] op_sel_hi:[1,0]
	v_pk_mul_f32 v[42:43], v[200:201], v[132:133] op_sel_hi:[1,0]
	v_add_f32_dpp v38, v38, v38 quad_perm:[1,0,3,2] row_mask:0xf bank_mask:0xf bound_ctrl:1
	v_pk_fma_f32 v[40:41], v[90:91], v[186:187], v[40:41]
	v_pk_fma_f32 v[42:43], v[88:89], v[188:189], v[42:43]
	v_add_f32_dpp v38, v38, v38 quad_perm:[2,3,0,1] row_mask:0xf bank_mask:0xf bound_ctrl:1
	v_pk_mul_f32 v[44:45], v[90:91], v[126:127]
	v_pk_fma_f32 v[44:45], v[88:89], v[128:129], v[44:45]
	v_add_f32_dpp v38, v38, v38 row_half_mirror row_mask:0xf bank_mask:0xf bound_ctrl:1
	v_add_f32_e32 v47, v44, v45
	s_nop 0
	v_add_f32_dpp v38, v38, v38 row_mirror row_mask:0xf bank_mask:0xf bound_ctrl:1
	v_pk_fma_f32 v[90:91], v[194:195], v[38:39], v[40:41] op_sel_hi:[1,0,1]
	v_pk_fma_f32 v[88:89], v[196:197], v[38:39], v[42:43] op_sel_hi:[1,0,1]
	ds_write2st64_b32 v96, v46, v47 offset0:216 offset1:220
	s_waitcnt lgkmcnt(1)
	v_pk_mul_f32 v[36:37], v[90:91], v[28:29]
	v_pk_fma_f32 v[36:37], v[88:89], v[30:31], v[36:37]
	v_add_f32_e32 v38, v36, v37
	v_pk_mul_f32 v[40:41], v[102:103], v[132:133] op_sel:[0,1] op_sel_hi:[1,1]
	v_pk_mul_f32 v[42:43], v[104:105], v[132:133] op_sel:[0,1] op_sel_hi:[1,1]
	v_add_f32_dpp v38, v38, v38 quad_perm:[1,0,3,2] row_mask:0xf bank_mask:0xf bound_ctrl:1
	v_pk_fma_f32 v[40:41], v[90:91], v[24:25], v[40:41]
	v_pk_fma_f32 v[42:43], v[88:89], v[26:27], v[42:43]
	v_add_f32_dpp v38, v38, v38 quad_perm:[2,3,0,1] row_mask:0xf bank_mask:0xf bound_ctrl:1
	v_pk_mul_f32 v[44:45], v[90:91], v[50:51]
	v_pk_fma_f32 v[44:45], v[88:89], v[52:53], v[44:45]
	v_add_f32_dpp v38, v38, v38 row_half_mirror row_mask:0xf bank_mask:0xf bound_ctrl:1
	v_add_f32_e32 v48, v44, v45
	s_nop 0
	v_add_f32_dpp v38, v38, v38 row_mirror row_mask:0xf bank_mask:0xf bound_ctrl:1
	v_pk_fma_f32 v[90:91], v[98:99], v[38:39], v[40:41] op_sel_hi:[1,0,1]
	v_pk_fma_f32 v[88:89], v[100:101], v[38:39], v[42:43] op_sel_hi:[1,0,1]
	v_pk_mul_f32 v[44:45], v[90:91], v[54:55]
	v_pk_fma_f32 v[44:45], v[88:89], v[56:57], v[44:45]
	v_add_f32_e32 v49, v44, v45
	ds_write2st64_b32 v96, v48, v49 offset0:224 offset1:228

.LBB0_660:
	s_andn2_saveexec_b64 s[46:47], s[46:47]
	s_cbranch_execz .LBB0_640
	v_add_u32_e32 v136, 0xa400, v95
	ds_read_b128 v[28:31], v92 offset:20736
	ds_read_b128 v[102:105], v92 offset:21248
	ds_read_b128 v[24:27], v92 offset:20480
	ds_read_b128 v[98:101], v92 offset:20992
	ds_read_b128 v[106:109], v92 offset:21504
	ds_read2_b32 v[130:131], v136 offset0:0 offset1:16
	ds_read_b128 v[114:117], v92 offset:22016
	ds_read_b128 v[122:125], v92 offset:22528
	ds_read_b128 v[110:113], v92 offset:21760
	ds_read_b128 v[118:121], v92 offset:22272
	ds_read_b128 v[126:129], v92 offset:22784
	ds_read_b128 v[190:193], v92 offset:23296
	ds_read_b128 v[198:201], v92 offset:23808
	ds_read_b128 v[186:189], v92 offset:23040
	ds_read_b128 v[194:197], v92 offset:23552
	ds_read_b128 v[50:53], v92 offset:24064
	ds_read2_b32 v[132:133], v136 offset0:32 offset1:48
	s_waitcnt lgkmcnt(11)
	v_pk_mul_f32 v[36:37], v[90:91], v[28:29]
	v_pk_fma_f32 v[36:37], v[88:89], v[30:31], v[36:37]
	v_add_f32_e32 v38, v36, v37
	v_pk_mul_f32 v[40:41], v[102:103], v[130:131] op_sel_hi:[1,0]
	v_pk_mul_f32 v[42:43], v[104:105], v[130:131] op_sel_hi:[1,0]
	v_add_f32_dpp v38, v38, v38 quad_perm:[1,0,3,2] row_mask:0xf bank_mask:0xf bound_ctrl:1
	v_pk_fma_f32 v[40:41], v[90:91], v[24:25], v[40:41]
	v_pk_fma_f32 v[42:43], v[88:89], v[26:27], v[42:43]
	v_add_f32_dpp v38, v38, v38 quad_perm:[2,3,0,1] row_mask:0xf bank_mask:0xf bound_ctrl:1
	s_nop 1
	v_add_f32_dpp v38, v38, v38 row_half_mirror row_mask:0xf bank_mask:0xf bound_ctrl:1
	s_nop 1
	v_add_f32_dpp v38, v38, v38 row_mirror row_mask:0xf bank_mask:0xf bound_ctrl:1
	v_pk_fma_f32 v[90:91], v[98:99], v[38:39], v[40:41] op_sel_hi:[1,0,1]
	v_pk_fma_f32 v[88:89], v[100:101], v[38:39], v[42:43] op_sel_hi:[1,0,1]
	ds_read_b128 v[28:31], v92 offset:24576
	ds_read_b128 v[102:105], v92 offset:25088
	ds_read_b128 v[24:27], v92 offset:24320
	ds_read_b128 v[98:101], v92 offset:24832
	ds_read_b128 v[54:57], v92 offset:25344
	s_waitcnt lgkmcnt(11)
	v_pk_mul_f32 v[36:37], v[90:91], v[114:115]
	v_pk_fma_f32 v[36:37], v[88:89], v[116:117], v[36:37]
	v_add_f32_e32 v38, v36, v37
	v_pk_mul_f32 v[40:41], v[122:123], v[130:131] op_sel:[0,1] op_sel_hi:[1,1]
	v_pk_mul_f32 v[42:43], v[124:125], v[130:131] op_sel:[0,1] op_sel_hi:[1,1]
	v_add_f32_dpp v38, v38, v38 quad_perm:[1,0,3,2] row_mask:0xf bank_mask:0xf bound_ctrl:1
	v_pk_fma_f32 v[40:41], v[90:91], v[110:111], v[40:41]
	v_pk_fma_f32 v[42:43], v[88:89], v[112:113], v[42:43]
	v_add_f32_dpp v38, v38, v38 quad_perm:[2,3,0,1] row_mask:0xf bank_mask:0xf bound_ctrl:1
	v_pk_mul_f32 v[44:45], v[90:91], v[106:107]
	v_pk_fma_f32 v[44:45], v[88:89], v[108:109], v[44:45]
	v_add_f32_dpp v38, v38, v38 row_half_mirror row_mask:0xf bank_mask:0xf bound_ctrl:1
	v_add_f32_e32 v46, v44, v45
	s_nop 0
	v_add_f32_dpp v38, v38, v38 row_mirror row_mask:0xf bank_mask:0xf bound_ctrl:1
	v_pk_fma_f32 v[90:91], v[118:119], v[38:39], v[40:41] op_sel_hi:[1,0,1]
	v_pk_fma_f32 v[88:89], v[120:121], v[38:39], v[42:43] op_sel_hi:[1,0,1]
	ds_read_b128 v[114:117], v92 offset:25856
	ds_read_b128 v[122:125], v92 offset:26368
	ds_read_b128 v[110:113], v92 offset:25600
	ds_read_b128 v[118:121], v92 offset:26112
	ds_read_b128 v[106:109], v92 offset:26624
	ds_read2_b32 v[130:131], v136 offset0:64 offset1:80
	s_waitcnt lgkmcnt(11)
	v_pk_mul_f32 v[36:37], v[90:91], v[190:191]
	v_pk_fma_f32 v[36:37], v[88:89], v[192:193], v[36:37]
	v_add_f32_e32 v38, v36, v37
	v_pk_mul_f32 v[40:41], v[198:199], v[132:133] op_sel_hi:[1,0]
	v_pk_mul_f32 v[42:43], v[200:201], v[132:133] op_sel_hi:[1,0]
	v_add_f32_dpp v38, v38, v38 quad_perm:[1,0,3,2] row_mask:0xf bank_mask:0xf bound_ctrl:1
	v_pk_fma_f32 v[40:41], v[90:91], v[186:187], v[40:41]
	v_pk_fma_f32 v[42:43], v[88:89], v[188:189], v[42:43]
	v_add_f32_dpp v38, v38, v38 quad_perm:[2,3,0,1] row_mask:0xf bank_mask:0xf bound_ctrl:1
	v_pk_mul_f32 v[44:45], v[90:91], v[126:127]
	v_pk_fma_f32 v[44:45], v[88:89], v[128:129], v[44:45]
	v_add_f32_dpp v38, v38, v38 row_half_mirror row_mask:0xf bank_mask:0xf bound_ctrl:1
	v_add_f32_e32 v47, v44, v45
	s_nop 0
	v_add_f32_dpp v38, v38, v38 row_mirror row_mask:0xf bank_mask:0xf bound_ctrl:1
	v_pk_fma_f32 v[90:91], v[194:195], v[38:39], v[40:41] op_sel_hi:[1,0,1]
	v_pk_fma_f32 v[88:89], v[196:197], v[38:39], v[42:43] op_sel_hi:[1,0,1]
	ds_read_b128 v[190:193], v92 offset:27136
	ds_read_b128 v[198:201], v92 offset:27648
	ds_read_b128 v[186:189], v92 offset:26880
	ds_read_b128 v[194:197], v92 offset:27392
	ds_read_b128 v[126:129], v92 offset:27904
	ds_write2st64_b32 v97, v46, v47 offset0:64 offset1:68
	s_waitcnt lgkmcnt(12)
	v_pk_mul_f32 v[36:37], v[90:91], v[28:29]
	v_pk_fma_f32 v[36:37], v[88:89], v[30:31], v[36:37]
	v_add_f32_e32 v38, v36, v37
	v_pk_mul_f32 v[40:41], v[102:103], v[132:133] op_sel:[0,1] op_sel_hi:[1,1]
	v_pk_mul_f32 v[42:43], v[104:105], v[132:133] op_sel:[0,1] op_sel_hi:[1,1]
	v_add_f32_dpp v38, v38, v38 quad_perm:[1,0,3,2] row_mask:0xf bank_mask:0xf bound_ctrl:1
	v_pk_fma_f32 v[40:41], v[90:91], v[24:25], v[40:41]
	v_pk_fma_f32 v[42:43], v[88:89], v[26:27], v[42:43]
	v_add_f32_dpp v38, v38, v38 quad_perm:[2,3,0,1] row_mask:0xf bank_mask:0xf bound_ctrl:1
	v_pk_mul_f32 v[44:45], v[90:91], v[50:51]
	v_pk_fma_f32 v[44:45], v[88:89], v[52:53], v[44:45]
	v_add_f32_dpp v38, v38, v38 row_half_mirror row_mask:0xf bank_mask:0xf bound_ctrl:1
	v_add_f32_e32 v48, v44, v45
	s_nop 0
	v_add_f32_dpp v38, v38, v38 row_mirror row_mask:0xf bank_mask:0xf bound_ctrl:1
	v_pk_fma_f32 v[90:91], v[98:99], v[38:39], v[40:41] op_sel_hi:[1,0,1]
	v_pk_fma_f32 v[88:89], v[100:101], v[38:39], v[42:43] op_sel_hi:[1,0,1]
	ds_read_b128 v[28:31], v92 offset:28416
	ds_read_b128 v[102:105], v92 offset:28928
	ds_read_b128 v[24:27], v92 offset:28160
	ds_read_b128 v[98:101], v92 offset:28672
	ds_read_b128 v[50:53], v92 offset:29184
	ds_read2_b32 v[132:133], v136 offset0:96 offset1:112
	s_waitcnt lgkmcnt(12)
	v_pk_mul_f32 v[36:37], v[90:91], v[114:115]
	v_pk_fma_f32 v[36:37], v[88:89], v[116:117], v[36:37]
	v_add_f32_e32 v38, v36, v37
	v_pk_mul_f32 v[40:41], v[122:123], v[130:131] op_sel_hi:[1,0]
	v_pk_mul_f32 v[42:43], v[124:125], v[130:131] op_sel_hi:[1,0]
	v_add_f32_dpp v38, v38, v38 quad_perm:[1,0,3,2] row_mask:0xf bank_mask:0xf bound_ctrl:1
	v_pk_fma_f32 v[40:41], v[90:91], v[110:111], v[40:41]
	v_pk_fma_f32 v[42:43], v[88:89], v[112:113], v[42:43]
	v_add_f32_dpp v38, v38, v38 quad_perm:[2,3,0,1] row_mask:0xf bank_mask:0xf bound_ctrl:1
	v_pk_mul_f32 v[44:45], v[90:91], v[54:55]
	v_pk_fma_f32 v[44:45], v[88:89], v[56:57], v[44:45]
	v_add_f32_dpp v38, v38, v38 row_half_mirror row_mask:0xf bank_mask:0xf bound_ctrl:1
	v_add_f32_e32 v49, v44, v45
	s_nop 0
	v_add_f32_dpp v38, v38, v38 row_mirror row_mask:0xf bank_mask:0xf bound_ctrl:1
	v_pk_fma_f32 v[90:91], v[118:119], v[38:39], v[40:41] op_sel_hi:[1,0,1]
	v_pk_fma_f32 v[88:89], v[120:121], v[38:39], v[42:43] op_sel_hi:[1,0,1]
	ds_read_b128 v[114:117], v92 offset:29696
	ds_read_b128 v[122:125], v92 offset:30208
	ds_read_b128 v[110:113], v92 offset:29440
	ds_read_b128 v[118:121], v92 offset:29952
	ds_read_b128 v[54:57], v92 offset:30464
	ds_write2st64_b32 v97, v48, v49 offset0:72 offset1:76
	s_waitcnt lgkmcnt(12)
	v_pk_mul_f32 v[36:37], v[90:91], v[190:191]
	v_pk_fma_f32 v[36:37], v[88:89], v[192:193], v[36:37]
	v_add_f32_e32 v38, v36, v37
	v_pk_mul_f32 v[40:41], v[198:199], v[130:131] op_sel:[0,1] op_sel_hi:[1,1]
	v_pk_mul_f32 v[42:43], v[200:201], v[130:131] op_sel:[0,1] op_sel_hi:[1,1]
	v_add_f32_dpp v38, v38, v38 quad_perm:[1,0,3,2] row_mask:0xf bank_mask:0xf bound_ctrl:1
	v_pk_fma_f32 v[40:41], v[90:91], v[186:187], v[40:41]
	v_pk_fma_f32 v[42:43], v[88:89], v[188:189], v[42:43]
	v_add_f32_dpp v38, v38, v38 quad_perm:[2,3,0,1] row_mask:0xf bank_mask:0xf bound_ctrl:1
	v_pk_mul_f32 v[44:45], v[90:91], v[106:107]
	v_pk_fma_f32 v[44:45], v[88:89], v[108:109], v[44:45]
	v_add_f32_dpp v38, v38, v38 row_half_mirror row_mask:0xf bank_mask:0xf bound_ctrl:1
	v_add_f32_e32 v46, v44, v45
	s_nop 0
	v_add_f32_dpp v38, v38, v38 row_mirror row_mask:0xf bank_mask:0xf bound_ctrl:1
	v_pk_fma_f32 v[90:91], v[194:195], v[38:39], v[40:41] op_sel_hi:[1,0,1]
	v_pk_fma_f32 v[88:89], v[196:197], v[38:39], v[42:43] op_sel_hi:[1,0,1]
	ds_read_b128 v[190:193], v92 offset:30976
	ds_read_b128 v[198:201], v92 offset:31488
	ds_read_b128 v[186:189], v92 offset:30720
	ds_read_b128 v[194:197], v92 offset:31232
	ds_read_b128 v[106:109], v92 offset:31744
	ds_read2_b32 v[130:131], v136 offset0:128 offset1:144
	s_waitcnt lgkmcnt(12)
	v_pk_mul_f32 v[36:37], v[90:91], v[28:29]
	v_pk_fma_f32 v[36:37], v[88:89], v[30:31], v[36:37]
	v_add_f32_e32 v38, v36, v37
	v_pk_mul_f32 v[40:41], v[102:103], v[132:133] op_sel_hi:[1,0]
	v_pk_mul_f32 v[42:43], v[104:105], v[132:133] op_sel_hi:[1,0]
	v_add_f32_dpp v38, v38, v38 quad_perm:[1,0,3,2] row_mask:0xf bank_mask:0xf bound_ctrl:1
	v_pk_fma_f32 v[40:41], v[90:91], v[24:25], v[40:41]
	v_pk_fma_f32 v[42:43], v[88:89], v[26:27], v[42:43]
	v_add_f32_dpp v38, v38, v38 quad_perm:[2,3,0,1] row_mask:0xf bank_mask:0xf bound_ctrl:1
	v_pk_mul_f32 v[44:45], v[90:91], v[126:127]
	v_pk_fma_f32 v[44:45], v[88:89], v[128:129], v[44:45]
	v_add_f32_dpp v38, v38, v38 row_half_mirror row_mask:0xf bank_mask:0xf bound_ctrl:1
	v_add_f32_e32 v47, v44, v45
	s_nop 0
	v_add_f32_dpp v38, v38, v38 row_mirror row_mask:0xf bank_mask:0xf bound_ctrl:1
	v_pk_fma_f32 v[90:91], v[98:99], v[38:39], v[40:41] op_sel_hi:[1,0,1]
	v_pk_fma_f32 v[88:89], v[100:101], v[38:39], v[42:43] op_sel_hi:[1,0,1]
	ds_read_b128 v[28:31], v92 offset:32256
	ds_read_b128 v[102:105], v92 offset:32768
	ds_read_b128 v[24:27], v92 offset:32000
	ds_read_b128 v[98:101], v92 offset:32512
	ds_read_b128 v[126:129], v92 offset:33024
	ds_write2st64_b32 v97, v46, v47 offset0:80 offset1:84
	s_waitcnt lgkmcnt(12)
	v_pk_mul_f32 v[36:37], v[90:91], v[114:115]
	v_pk_fma_f32 v[36:37], v[88:89], v[116:117], v[36:37]
	v_add_f32_e32 v38, v36, v37
	v_pk_mul_f32 v[40:41], v[122:123], v[132:133] op_sel:[0,1] op_sel_hi:[1,1]
	v_pk_mul_f32 v[42:43], v[124:125], v[132:133] op_sel:[0,1] op_sel_hi:[1,1]
	v_add_f32_dpp v38, v38, v38 quad_perm:[1,0,3,2] row_mask:0xf bank_mask:0xf bound_ctrl:1
	v_pk_fma_f32 v[40:41], v[90:91], v[110:111], v[40:41]
	v_pk_fma_f32 v[42:43], v[88:89], v[112:113], v[42:43]
	v_add_f32_dpp v38, v38, v38 quad_perm:[2,3,0,1] row_mask:0xf bank_mask:0xf bound_ctrl:1
	v_pk_mul_f32 v[44:45], v[90:91], v[50:51]
	v_pk_fma_f32 v[44:45], v[88:89], v[52:53], v[44:45]
	v_add_f32_dpp v38, v38, v38 row_half_mirror row_mask:0xf bank_mask:0xf bound_ctrl:1
	v_add_f32_e32 v48, v44, v45
	s_nop 0
	v_add_f32_dpp v38, v38, v38 row_mirror row_mask:0xf bank_mask:0xf bound_ctrl:1
	v_pk_fma_f32 v[90:91], v[118:119], v[38:39], v[40:41] op_sel_hi:[1,0,1]
	v_pk_fma_f32 v[88:89], v[120:121], v[38:39], v[42:43] op_sel_hi:[1,0,1]
	ds_read_b128 v[114:117], v92 offset:33536
	ds_read_b128 v[122:125], v92 offset:34048
	ds_read_b128 v[110:113], v92 offset:33280
	ds_read_b128 v[118:121], v92 offset:33792
	ds_read_b128 v[50:53], v92 offset:34304
	ds_read2_b32 v[132:133], v136 offset0:160 offset1:176
	s_waitcnt lgkmcnt(12)
	v_pk_mul_f32 v[36:37], v[90:91], v[190:191]
	v_pk_fma_f32 v[36:37], v[88:89], v[192:193], v[36:37]
	v_add_f32_e32 v38, v36, v37
	v_pk_mul_f32 v[40:41], v[198:199], v[130:131] op_sel_hi:[1,0]
	v_pk_mul_f32 v[42:43], v[200:201], v[130:131] op_sel_hi:[1,0]
	v_add_f32_dpp v38, v38, v38 quad_perm:[1,0,3,2] row_mask:0xf bank_mask:0xf bound_ctrl:1
	v_pk_fma_f32 v[40:41], v[90:91], v[186:187], v[40:41]
	v_pk_fma_f32 v[42:43], v[88:89], v[188:189], v[42:43]
	v_add_f32_dpp v38, v38, v38 quad_perm:[2,3,0,1] row_mask:0xf bank_mask:0xf bound_ctrl:1
	v_pk_mul_f32 v[44:45], v[90:91], v[54:55]
	v_pk_fma_f32 v[44:45], v[88:89], v[56:57], v[44:45]
	v_add_f32_dpp v38, v38, v38 row_half_mirror row_mask:0xf bank_mask:0xf bound_ctrl:1
	v_add_f32_e32 v49, v44, v45
	s_nop 0
	v_add_f32_dpp v38, v38, v38 row_mirror row_mask:0xf bank_mask:0xf bound_ctrl:1
	v_pk_fma_f32 v[90:91], v[194:195], v[38:39], v[40:41] op_sel_hi:[1,0,1]
	v_pk_fma_f32 v[88:89], v[196:197], v[38:39], v[42:43] op_sel_hi:[1,0,1]
	ds_read_b128 v[190:193], v92 offset:34816
	ds_read_b128 v[198:201], v92 offset:35328
	ds_read_b128 v[186:189], v92 offset:34560
	ds_read_b128 v[194:197], v92 offset:35072
	ds_read_b128 v[54:57], v92 offset:35584
	ds_write2st64_b32 v97, v48, v49 offset0:88 offset1:92
	s_waitcnt lgkmcnt(12)
	v_pk_mul_f32 v[36:37], v[90:91], v[28:29]
	v_pk_fma_f32 v[36:37], v[88:89], v[30:31], v[36:37]
	v_add_f32_e32 v38, v36, v37
	v_pk_mul_f32 v[40:41], v[102:103], v[130:131] op_sel:[0,1] op_sel_hi:[1,1]
	v_pk_mul_f32 v[42:43], v[104:105], v[130:131] op_sel:[0,1] op_sel_hi:[1,1]
	v_add_f32_dpp v38, v38, v38 quad_perm:[1,0,3,2] row_mask:0xf bank_mask:0xf bound_ctrl:1
	v_pk_fma_f32 v[40:41], v[90:91], v[24:25], v[40:41]
	v_pk_fma_f32 v[42:43], v[88:89], v[26:27], v[42:43]
	v_add_f32_dpp v38, v38, v38 quad_perm:[2,3,0,1] row_mask:0xf bank_mask:0xf bound_ctrl:1
	v_pk_mul_f32 v[44:45], v[90:91], v[106:107]
	v_pk_fma_f32 v[44:45], v[88:89], v[108:109], v[44:45]
	v_add_f32_dpp v38, v38, v38 row_half_mirror row_mask:0xf bank_mask:0xf bound_ctrl:1
	v_add_f32_e32 v46, v44, v45
	s_nop 0
	v_add_f32_dpp v38, v38, v38 row_mirror row_mask:0xf bank_mask:0xf bound_ctrl:1
	v_pk_fma_f32 v[90:91], v[98:99], v[38:39], v[40:41] op_sel_hi:[1,0,1]
	v_pk_fma_f32 v[88:89], v[100:101], v[38:39], v[42:43] op_sel_hi:[1,0,1]
	ds_read_b128 v[28:31], v92 offset:36096
	ds_read_b128 v[102:105], v92 offset:36608
	ds_read_b128 v[24:27], v92 offset:35840
	ds_read_b128 v[98:101], v92 offset:36352
	ds_read_b128 v[106:109], v92 offset:36864
	ds_read2_b32 v[130:131], v136 offset0:192 offset1:208
	s_waitcnt lgkmcnt(12)
	v_pk_mul_f32 v[36:37], v[90:91], v[114:115]
	v_pk_fma_f32 v[36:37], v[88:89], v[116:117], v[36:37]
	v_add_f32_e32 v38, v36, v37
	v_pk_mul_f32 v[40:41], v[122:123], v[132:133] op_sel_hi:[1,0]
	v_pk_mul_f32 v[42:43], v[124:125], v[132:133] op_sel_hi:[1,0]
	v_add_f32_dpp v38, v38, v38 quad_perm:[1,0,3,2] row_mask:0xf bank_mask:0xf bound_ctrl:1
	v_pk_fma_f32 v[40:41], v[90:91], v[110:111], v[40:41]
	v_pk_fma_f32 v[42:43], v[88:89], v[112:113], v[42:43]
	v_add_f32_dpp v38, v38, v38 quad_perm:[2,3,0,1] row_mask:0xf bank_mask:0xf bound_ctrl:1
	v_pk_mul_f32 v[44:45], v[90:91], v[126:127]
	v_pk_fma_f32 v[44:45], v[88:89], v[128:129], v[44:45]
	v_add_f32_dpp v38, v38, v38 row_half_mirror row_mask:0xf bank_mask:0xf bound_ctrl:1
	v_add_f32_e32 v47, v44, v45
	s_nop 0
	v_add_f32_dpp v38, v38, v38 row_mirror row_mask:0xf bank_mask:0xf bound_ctrl:1
	v_pk_fma_f32 v[90:91], v[118:119], v[38:39], v[40:41] op_sel_hi:[1,0,1]
	v_pk_fma_f32 v[88:89], v[120:121], v[38:39], v[42:43] op_sel_hi:[1,0,1]
	ds_read_b128 v[114:117], v92 offset:37376
	ds_read_b128 v[122:125], v92 offset:37888
	ds_read_b128 v[110:113], v92 offset:37120
	ds_read_b128 v[118:121], v92 offset:37632
	ds_read_b128 v[126:129], v92 offset:38144
	ds_write2st64_b32 v97, v46, v47 offset0:96 offset1:100
	s_waitcnt lgkmcnt(12)
	v_pk_mul_f32 v[36:37], v[90:91], v[190:191]
	v_pk_fma_f32 v[36:37], v[88:89], v[192:193], v[36:37]
	v_add_f32_e32 v38, v36, v37
	v_pk_mul_f32 v[40:41], v[198:199], v[132:133] op_sel:[0,1] op_sel_hi:[1,1]
	v_pk_mul_f32 v[42:43], v[200:201], v[132:133] op_sel:[0,1] op_sel_hi:[1,1]
	v_add_f32_dpp v38, v38, v38 quad_perm:[1,0,3,2] row_mask:0xf bank_mask:0xf bound_ctrl:1
	v_pk_fma_f32 v[40:41], v[90:91], v[186:187], v[40:41]
	v_pk_fma_f32 v[42:43], v[88:89], v[188:189], v[42:43]
	v_add_f32_dpp v38, v38, v38 quad_perm:[2,3,0,1] row_mask:0xf bank_mask:0xf bound_ctrl:1
	v_pk_mul_f32 v[44:45], v[90:91], v[50:51]
	v_pk_fma_f32 v[44:45], v[88:89], v[52:53], v[44:45]
	v_add_f32_dpp v38, v38, v38 row_half_mirror row_mask:0xf bank_mask:0xf bound_ctrl:1
	v_add_f32_e32 v48, v44, v45
	s_nop 0
	v_add_f32_dpp v38, v38, v38 row_mirror row_mask:0xf bank_mask:0xf bound_ctrl:1
	v_pk_fma_f32 v[90:91], v[194:195], v[38:39], v[40:41] op_sel_hi:[1,0,1]
	v_pk_fma_f32 v[88:89], v[196:197], v[38:39], v[42:43] op_sel_hi:[1,0,1]
	ds_read_b128 v[190:193], v92 offset:38656
	ds_read_b128 v[198:201], v92 offset:39168
	ds_read_b128 v[186:189], v92 offset:38400
	ds_read_b128 v[194:197], v92 offset:38912
	ds_read_b128 v[50:53], v92 offset:39424
	ds_read2_b32 v[132:133], v136 offset0:224 offset1:240
	s_waitcnt lgkmcnt(12)
	v_pk_mul_f32 v[36:37], v[90:91], v[28:29]
	v_pk_fma_f32 v[36:37], v[88:89], v[30:31], v[36:37]
	v_add_f32_e32 v38, v36, v37
	v_pk_mul_f32 v[40:41], v[102:103], v[130:131] op_sel_hi:[1,0]
	v_pk_mul_f32 v[42:43], v[104:105], v[130:131] op_sel_hi:[1,0]
	v_add_f32_dpp v38, v38, v38 quad_perm:[1,0,3,2] row_mask:0xf bank_mask:0xf bound_ctrl:1
	v_pk_fma_f32 v[40:41], v[90:91], v[24:25], v[40:41]
	v_pk_fma_f32 v[42:43], v[88:89], v[26:27], v[42:43]
	v_add_f32_dpp v38, v38, v38 quad_perm:[2,3,0,1] row_mask:0xf bank_mask:0xf bound_ctrl:1
	v_pk_mul_f32 v[44:45], v[90:91], v[54:55]
	v_pk_fma_f32 v[44:45], v[88:89], v[56:57], v[44:45]
	v_add_f32_dpp v38, v38, v38 row_half_mirror row_mask:0xf bank_mask:0xf bound_ctrl:1
	v_add_f32_e32 v49, v44, v45
	s_nop 0
	v_add_f32_dpp v38, v38, v38 row_mirror row_mask:0xf bank_mask:0xf bound_ctrl:1
	v_pk_fma_f32 v[90:91], v[98:99], v[38:39], v[40:41] op_sel_hi:[1,0,1]
	v_pk_fma_f32 v[88:89], v[100:101], v[38:39], v[42:43] op_sel_hi:[1,0,1]
	ds_read_b128 v[28:31], v92 offset:39936
	ds_read_b128 v[102:105], v92 offset:40448
	ds_read_b128 v[24:27], v92 offset:39680
	ds_read_b128 v[98:101], v92 offset:40192
	ds_read_b128 v[54:57], v92 offset:40704
	ds_write2st64_b32 v97, v48, v49 offset0:104 offset1:108
	s_waitcnt lgkmcnt(12)
	v_pk_mul_f32 v[36:37], v[90:91], v[114:115]
	v_pk_fma_f32 v[36:37], v[88:89], v[116:117], v[36:37]
	v_add_f32_e32 v38, v36, v37
	v_pk_mul_f32 v[40:41], v[122:123], v[130:131] op_sel:[0,1] op_sel_hi:[1,1]
	v_pk_mul_f32 v[42:43], v[124:125], v[130:131] op_sel:[0,1] op_sel_hi:[1,1]
	v_add_f32_dpp v38, v38, v38 quad_perm:[1,0,3,2] row_mask:0xf bank_mask:0xf bound_ctrl:1
	v_pk_fma_f32 v[40:41], v[90:91], v[110:111], v[40:41]
	v_pk_fma_f32 v[42:43], v[88:89], v[112:113], v[42:43]
	v_add_f32_dpp v38, v38, v38 quad_perm:[2,3,0,1] row_mask:0xf bank_mask:0xf bound_ctrl:1
	v_pk_mul_f32 v[44:45], v[90:91], v[106:107]
	v_pk_fma_f32 v[44:45], v[88:89], v[108:109], v[44:45]
	v_add_f32_dpp v38, v38, v38 row_half_mirror row_mask:0xf bank_mask:0xf bound_ctrl:1
	v_add_f32_e32 v46, v44, v45
	s_nop 0
	v_add_f32_dpp v38, v38, v38 row_mirror row_mask:0xf bank_mask:0xf bound_ctrl:1
	v_pk_fma_f32 v[90:91], v[118:119], v[38:39], v[40:41] op_sel_hi:[1,0,1]
	v_pk_fma_f32 v[88:89], v[120:121], v[38:39], v[42:43] op_sel_hi:[1,0,1]
	s_waitcnt lgkmcnt(6)
	v_pk_mul_f32 v[36:37], v[90:91], v[190:191]
	v_pk_fma_f32 v[36:37], v[88:89], v[192:193], v[36:37]
	v_add_f32_e32 v38, v36, v37
	v_pk_mul_f32 v[40:41], v[198:199], v[132:133] op_sel_hi:[1,0]
	v_pk_mul_f32 v[42:43], v[200:201], v[132:133] op_sel_hi:[1,0]
	v_add_f32_dpp v38, v38, v38 quad_perm:[1,0,3,2] row_mask:0xf bank_mask:0xf bound_ctrl:1
	v_pk_fma_f32 v[40:41], v[90:91], v[186:187], v[40:41]
	v_pk_fma_f32 v[42:43], v[88:89], v[188:189], v[42:43]
	v_add_f32_dpp v38, v38, v38 quad_perm:[2,3,0,1] row_mask:0xf bank_mask:0xf bound_ctrl:1
	v_pk_mul_f32 v[44:45], v[90:91], v[126:127]
	v_pk_fma_f32 v[44:45], v[88:89], v[128:129], v[44:45]
	v_add_f32_dpp v38, v38, v38 row_half_mirror row_mask:0xf bank_mask:0xf bound_ctrl:1
	v_add_f32_e32 v47, v44, v45
	s_nop 0
	v_add_f32_dpp v38, v38, v38 row_mirror row_mask:0xf bank_mask:0xf bound_ctrl:1
	v_pk_fma_f32 v[90:91], v[194:195], v[38:39], v[40:41] op_sel_hi:[1,0,1]
	v_pk_fma_f32 v[88:89], v[196:197], v[38:39], v[42:43] op_sel_hi:[1,0,1]
	ds_write2st64_b32 v97, v46, v47 offset0:112 offset1:116
	s_waitcnt lgkmcnt(1)
	v_pk_mul_f32 v[36:37], v[90:91], v[28:29]
	v_pk_fma_f32 v[36:37], v[88:89], v[30:31], v[36:37]
	v_add_f32_e32 v38, v36, v37
	v_pk_mul_f32 v[40:41], v[102:103], v[132:133] op_sel:[0,1] op_sel_hi:[1,1]
	v_pk_mul_f32 v[42:43], v[104:105], v[132:133] op_sel:[0,1] op_sel_hi:[1,1]
	v_add_f32_dpp v38, v38, v38 quad_perm:[1,0,3,2] row_mask:0xf bank_mask:0xf bound_ctrl:1
	v_pk_fma_f32 v[40:41], v[90:91], v[24:25], v[40:41]
	v_pk_fma_f32 v[42:43], v[88:89], v[26:27], v[42:43]
	v_add_f32_dpp v38, v38, v38 quad_perm:[2,3,0,1] row_mask:0xf bank_mask:0xf bound_ctrl:1
	v_pk_mul_f32 v[44:45], v[90:91], v[50:51]
	v_pk_fma_f32 v[44:45], v[88:89], v[52:53], v[44:45]
	v_add_f32_dpp v38, v38, v38 row_half_mirror row_mask:0xf bank_mask:0xf bound_ctrl:1
	v_add_f32_e32 v48, v44, v45
	s_nop 0
	v_add_f32_dpp v38, v38, v38 row_mirror row_mask:0xf bank_mask:0xf bound_ctrl:1
	v_pk_fma_f32 v[90:91], v[98:99], v[38:39], v[40:41] op_sel_hi:[1,0,1]
	v_pk_fma_f32 v[88:89], v[100:101], v[38:39], v[42:43] op_sel_hi:[1,0,1]
	v_pk_mul_f32 v[44:45], v[90:91], v[54:55]
	v_pk_fma_f32 v[44:45], v[88:89], v[56:57], v[44:45]
	v_add_f32_e32 v49, v44, v45
	ds_write2st64_b32 v97, v48, v49 offset0:120 offset1:124
	s_branch .LBB0_640
